# attention QK^T: window masking and running max of finished score blocks issued in the MFMA shadow (two blocks behind)
# speedup vs baseline: 1.0027x; 1.0027x over previous
; #define LAS __attribute__((address_space(3)))
; __device__ __forceinline__ void attn_item(const Params& P, int half, int item, LAS unsigned char* lds, unsigned* ctr) {
;     ...
;     const int m0 = (16 * w < 96) ? 16 * w : 96;
;     f32x4 S[10];
; #pragma unroll
;     for (int jt = 0; jt < 10; ++jt) {
;         S[jt] = (f32x4){0.f, 0.f, 0.f, 0.f};
;         const LAS unsigned char* kr = Ks + (m0 + jt * 16 + c) * KSTR + 16 * g;
; #pragma unroll
;         for (int ks = 0; ks < 4; ++ks) { const bf16x8 a = *(const LAS bf16x8*)(kr + ks * 64); S[jt] = __builtin_amdgcn_mfma_f32_16x16x32_bf16(a, Qf[ks], S[jt], 0, 0, 0); }
;     }
;     float mx = -INFINITY;
;     const int dbase = qi + 128 - m0 - 4 * g;
;     const unsigned dlim = (unsigned)((n == 0) ? (qi < 128 ? qi : 128) : 128);
; #pragma unroll
;     for (int jt = 0; jt < 10; ++jt)
; #pragma unroll
;         for (int jj = 0; jj < 4; ++jj) { const bool ok = (unsigned)(dbase - (jt * 16 + jj)) <= dlim;
;             const float s = ok ? S[jt][jj] : -INFINITY; S[jt][jj] = s; mx = fmaxf(mx, s); }
.LBB0_539:
	s_or_b64 exec, exec, s[30:31]
	s_and_b32 s6, s6, -16
	v_and_b32_e32 v54, 15, v137
	s_min_i32 s6, s6, 0x60
	v_or_b32_e32 v18, s6, v54
	s_movk_i32 s7, 0x110
	v_mul_lo_u32 v18, v18, s7
	v_add3_u32 v55, 0, v194, v18
	ds_read_b128 v[204:207], v55
	ds_read_b128 v[208:211], v55 offset:64
	ds_read_b128 v[212:215], v55 offset:4416
	ds_read_b128 v[216:219], v55 offset:8768
	ds_read_b128 v[220:223], v55 offset:13120
	ds_read_b128 v[224:227], v55 offset:128
	s_and_b32 s5, s5, 0xff
	s_cmp_eq_u32 s5, 0
	s_cselect_b64 vcc, -1, 0
	s_mov_b32 s5, 0xff800000
	v_lshlrev_b32_e32 v194, 3, v136
	v_lshlrev_b32_e32 v150, 2, v136
	v_or_b32_e32 v150, s6, v150
	v_min_i32_e32 v148, 0x80, v138
	v_mov_b32_e32 v151, 0x80
	v_cndmask_b32_e32 v148, v151, v148, vcc
	v_sub_u32_e32 v149, v138, v150
	s_waitcnt lgkmcnt(5)
	v_mfma_f32_16x16x32_bf16 v[18:21], v[204:207], v[6:9], 0
	ds_read_b128 v[204:207], v55 offset:17472
	ds_read_b128 v[236:239], v55 offset:21824
	ds_read_b128 v[240:243], v55 offset:192
	s_waitcnt lgkmcnt(7)
	v_mfma_f32_16x16x32_bf16 v[18:21], v[208:211], v[14:17], v[18:21]
	ds_read_b128 v[208:211], v55 offset:26176
	ds_read_b128 v[244:247], v55 offset:30528
	ds_read_b128 v[176:179], v55 offset:4352
	s_waitcnt lgkmcnt(6)
	v_mfma_f32_16x16x32_bf16 v[18:21], v[224:227], v[2:5], v[18:21]
	ds_read_b128 v[224:227], v55 offset:34880
	ds_read_b128 v[180:183], v55 offset:4480
	ds_read_b128 v[184:187], v55 offset:4544
	s_waitcnt lgkmcnt(6)
	v_mfma_f32_16x16x32_bf16 v[18:21], v[240:243], v[10:13], v[18:21]
	ds_read_b128 v[240:243], v55 offset:8704
	ds_read_b128 v[188:191], v55 offset:8832
	s_waitcnt lgkmcnt(5)
	v_mfma_f32_16x16x32_bf16 v[22:25], v[176:179], v[6:9], 0
	v_mfma_f32_16x16x32_bf16 v[22:25], v[212:215], v[14:17], v[22:25]
	ds_read_b128 v[212:215], v55 offset:8896
	s_waitcnt lgkmcnt(4)
	v_mfma_f32_16x16x32_bf16 v[22:25], v[180:183], v[2:5], v[22:25]
	ds_read_b128 v[176:179], v55 offset:13056
	s_waitcnt lgkmcnt(4)
	v_mfma_f32_16x16x32_bf16 v[22:25], v[184:187], v[10:13], v[22:25]
	ds_read_b128 v[180:183], v55 offset:13184
	s_waitcnt lgkmcnt(4)
	v_mfma_f32_16x16x32_bf16 v[26:29], v[240:243], v[6:9], 0
	v_add_u32_e32 v151, 0x80, v149
	v_cmp_le_u32_e32 vcc, v151, v148
	s_nop 1
	v_cndmask_b32_e32 v160, v235, v18, vcc
	v_mfma_f32_16x16x32_bf16 v[26:29], v[216:219], v[14:17], v[26:29]
	v_add_u32_e32 v151, 0x7f, v149
	v_cmp_le_u32_e32 vcc, v151, v148
	s_nop 1
	v_cndmask_b32_e32 v161, v235, v19, vcc
	v_max3_f32 v159, v160, s5, v161
	ds_read_b128 v[216:219], v55 offset:13248
	s_waitcnt lgkmcnt(4)
	v_mfma_f32_16x16x32_bf16 v[26:29], v[188:191], v[2:5], v[26:29]
	v_add_u32_e32 v151, 0x7e, v149
	v_cmp_le_u32_e32 vcc, v151, v148
	s_nop 1
	v_cndmask_b32_e32 v162, v235, v20, vcc
	ds_read_b128 v[240:243], v55 offset:17408
	s_waitcnt lgkmcnt(4)
	v_mfma_f32_16x16x32_bf16 v[26:29], v[212:215], v[10:13], v[26:29]
	v_add_u32_e32 v151, 0x7d, v149
	v_cmp_le_u32_e32 vcc, v151, v148
	s_nop 1
	v_cndmask_b32_e32 v163, v235, v21, vcc
	v_max3_f32 v159, v159, v162, v163
	ds_read_b128 v[212:215], v55 offset:17536
	s_waitcnt lgkmcnt(4)
	v_mfma_f32_16x16x32_bf16 v[30:33], v[176:179], v[6:9], 0
	v_add_u32_e32 v151, 0x70, v149
	v_cmp_le_u32_e32 vcc, v151, v148
	s_nop 1
	v_cndmask_b32_e32 v164, v235, v22, vcc
	v_mfma_f32_16x16x32_bf16 v[30:33], v[220:223], v[14:17], v[30:33]
	v_add_u32_e32 v151, 0x6f, v149
	v_cmp_le_u32_e32 vcc, v151, v148
	s_nop 1
	v_cndmask_b32_e32 v165, v235, v23, vcc
	v_max3_f32 v159, v159, v164, v165
	ds_read_b128 v[220:223], v55 offset:17600
	s_waitcnt lgkmcnt(4)
	v_mfma_f32_16x16x32_bf16 v[30:33], v[180:183], v[2:5], v[30:33]
	v_add_u32_e32 v151, 0x6e, v149
	v_cmp_le_u32_e32 vcc, v151, v148
	s_nop 1
	v_cndmask_b32_e32 v168, v235, v24, vcc
	ds_read_b128 v[176:179], v55 offset:21760
	s_waitcnt lgkmcnt(4)
	v_mfma_f32_16x16x32_bf16 v[30:33], v[216:219], v[10:13], v[30:33]
	v_add_u32_e32 v151, 0x6d, v149
	v_cmp_le_u32_e32 vcc, v151, v148
	s_nop 1
	v_cndmask_b32_e32 v169, v235, v25, vcc
	v_max3_f32 v159, v159, v168, v169
	ds_read_b128 v[216:219], v55 offset:21888
	s_waitcnt lgkmcnt(4)
	v_mfma_f32_16x16x32_bf16 v[34:37], v[240:243], v[6:9], 0
	v_add_u32_e32 v151, 0x60, v149
	v_cmp_le_u32_e32 vcc, v151, v148
	s_nop 1
	v_cndmask_b32_e32 v18, v235, v26, vcc
	v_mfma_f32_16x16x32_bf16 v[34:37], v[204:207], v[14:17], v[34:37]
	v_add_u32_e32 v151, 0x5f, v149
	v_cmp_le_u32_e32 vcc, v151, v148
	s_nop 1
	v_cndmask_b32_e32 v19, v235, v27, vcc
	v_max3_f32 v159, v159, v18, v19
	ds_read_b128 v[204:207], v55 offset:21952
	s_waitcnt lgkmcnt(4)
	v_mfma_f32_16x16x32_bf16 v[34:37], v[212:215], v[2:5], v[34:37]
	v_add_u32_e32 v151, 0x5e, v149
	v_cmp_le_u32_e32 vcc, v151, v148
	s_nop 1
	v_cndmask_b32_e32 v20, v235, v28, vcc
	ds_read_b128 v[212:215], v55 offset:26112
	s_waitcnt lgkmcnt(4)
	v_mfma_f32_16x16x32_bf16 v[34:37], v[220:223], v[10:13], v[34:37]
	v_add_u32_e32 v151, 0x5d, v149
	v_cmp_le_u32_e32 vcc, v151, v148
	s_nop 1
	v_cndmask_b32_e32 v21, v235, v29, vcc
	v_max3_f32 v159, v159, v20, v21
	ds_read_b128 v[220:223], v55 offset:26240
	s_waitcnt lgkmcnt(4)
	v_mfma_f32_16x16x32_bf16 v[38:41], v[176:179], v[6:9], 0
	v_add_u32_e32 v151, 0x50, v149
	v_cmp_le_u32_e32 vcc, v151, v148
	s_nop 1
	v_cndmask_b32_e32 v22, v235, v30, vcc
	v_mfma_f32_16x16x32_bf16 v[38:41], v[236:239], v[14:17], v[38:41]
	v_add_u32_e32 v151, 0x4f, v149
	v_cmp_le_u32_e32 vcc, v151, v148
	s_nop 1
	v_cndmask_b32_e32 v25, v235, v31, vcc
	v_max3_f32 v159, v159, v22, v25
	ds_read_b128 v[236:239], v55 offset:26304
	s_waitcnt lgkmcnt(4)
	v_mfma_f32_16x16x32_bf16 v[38:41], v[216:219], v[2:5], v[38:41]
	v_add_u32_e32 v151, 0x4e, v149
	v_cmp_le_u32_e32 vcc, v151, v148
	s_nop 1
	v_cndmask_b32_e32 v26, v235, v32, vcc
	ds_read_b128 v[216:219], v55 offset:30464
	s_waitcnt lgkmcnt(4)
; #define LAS __attribute__((address_space(3)))
; __device__ __forceinline__ void attn_item(const Params& P, int half, int item, LAS unsigned char* lds, unsigned* ctr) {
;     ...
;         for (int ks = 0; ks < 4; ++ks) { const bf16x8 a = *(const LAS bf16x8*)(kr + ks * 64); S[jt] = __builtin_amdgcn_mfma_f32_16x16x32_bf16(a, Qf[ks], S[jt], 0, 0, 0); }
;     }
;     float mx = -INFINITY;
;     const int dbase = qi + 128 - m0 - 4 * g;
;     const unsigned dlim = (unsigned)((n == 0) ? (qi < 128 ? qi : 128) : 128);
; #pragma unroll
;     for (int jt = 0; jt < 10; ++jt)
; #pragma unroll
;         for (int jj = 0; jj < 4; ++jj) { const bool ok = (unsigned)(dbase - (jt * 16 + jj)) <= dlim;
;             const float s = ok ? S[jt][jj] : -INFINITY; S[jt][jj] = s; mx = fmaxf(mx, s); }
;     mx = fmaxf(mx, __shfl_xor(mx, 16)); mx = fmaxf(mx, __shfl_xor(mx, 32));
	v_mfma_f32_16x16x32_bf16 v[38:41], v[204:207], v[10:13], v[38:41]
	v_add_u32_e32 v151, 0x4d, v149
	v_cmp_le_u32_e32 vcc, v151, v148
	s_nop 1
	v_cndmask_b32_e32 v27, v235, v33, vcc
	v_max3_f32 v159, v159, v26, v27
	ds_read_b128 v[204:207], v55 offset:30592
	s_waitcnt lgkmcnt(4)
	v_mfma_f32_16x16x32_bf16 v[42:45], v[212:215], v[6:9], 0
	v_add_u32_e32 v151, 64, v149
	v_cmp_le_u32_e32 vcc, v151, v148
	s_nop 1
	v_cndmask_b32_e32 v28, v235, v34, vcc
	v_mfma_f32_16x16x32_bf16 v[42:45], v[208:211], v[14:17], v[42:45]
	v_add_u32_e32 v151, 63, v149
	v_cmp_le_u32_e32 vcc, v151, v148
	s_nop 1
	v_cndmask_b32_e32 v29, v235, v35, vcc
	v_max3_f32 v159, v159, v28, v29
	ds_read_b128 v[208:211], v55 offset:30656
	s_waitcnt lgkmcnt(4)
	v_mfma_f32_16x16x32_bf16 v[42:45], v[220:223], v[2:5], v[42:45]
	v_add_u32_e32 v151, 62, v149
	v_cmp_le_u32_e32 vcc, v151, v148
	s_nop 1
	v_cndmask_b32_e32 v30, v235, v36, vcc
	ds_read_b128 v[212:215], v55 offset:34816
	s_waitcnt lgkmcnt(4)
	v_mfma_f32_16x16x32_bf16 v[42:45], v[236:239], v[10:13], v[42:45]
	v_add_u32_e32 v151, 61, v149
	v_cmp_le_u32_e32 vcc, v151, v148
	s_nop 1
	v_cndmask_b32_e32 v31, v235, v37, vcc
	v_max3_f32 v159, v159, v30, v31
	ds_read_b128 v[220:223], v55 offset:34944
	s_waitcnt lgkmcnt(4)
	v_mfma_f32_16x16x32_bf16 v[46:49], v[216:219], v[6:9], 0
	v_add_u32_e32 v151, 48, v149
	v_cmp_le_u32_e32 vcc, v151, v148
	s_nop 1
	v_cndmask_b32_e32 v34, v235, v38, vcc
	v_mfma_f32_16x16x32_bf16 v[46:49], v[244:247], v[14:17], v[46:49]
	v_add_u32_e32 v151, 47, v149
	v_cmp_le_u32_e32 vcc, v151, v148
	s_nop 1
	v_cndmask_b32_e32 v35, v235, v39, vcc
	v_max3_f32 v159, v159, v34, v35
	ds_read_b128 v[216:219], v55 offset:35008
	s_waitcnt lgkmcnt(4)
	v_mfma_f32_16x16x32_bf16 v[46:49], v[204:207], v[2:5], v[46:49]
	v_add_u32_e32 v151, 46, v149
	v_cmp_le_u32_e32 vcc, v151, v148
	s_nop 1
	v_cndmask_b32_e32 v36, v235, v40, vcc
	ds_read_b128 v[204:207], v55 offset:39168
	s_waitcnt lgkmcnt(4)
	v_mfma_f32_16x16x32_bf16 v[46:49], v[208:211], v[10:13], v[46:49]
	v_add_u32_e32 v151, 45, v149
	v_cmp_le_u32_e32 vcc, v151, v148
	s_nop 1
	v_cndmask_b32_e32 v37, v235, v41, vcc
	v_max3_f32 v159, v159, v36, v37
	ds_read_b128 v[208:211], v55 offset:39232
	s_waitcnt lgkmcnt(4)
	v_mfma_f32_16x16x32_bf16 v[50:53], v[212:215], v[6:9], 0
	v_add_u32_e32 v151, 32, v149
	v_cmp_le_u32_e32 vcc, v151, v148
	s_nop 1
	v_cndmask_b32_e32 v38, v235, v42, vcc
	v_mfma_f32_16x16x32_bf16 v[50:53], v[224:227], v[14:17], v[50:53]
	v_add_u32_e32 v151, 31, v149
	v_cmp_le_u32_e32 vcc, v151, v148
	s_nop 1
	v_cndmask_b32_e32 v39, v235, v43, vcc
	v_max3_f32 v159, v159, v38, v39
	ds_read_b128 v[212:215], v55 offset:39296
	s_waitcnt lgkmcnt(4)
	v_mfma_f32_16x16x32_bf16 v[50:53], v[220:223], v[2:5], v[50:53]
	v_add_u32_e32 v151, 30, v149
	v_cmp_le_u32_e32 vcc, v151, v148
	s_nop 1
	v_cndmask_b32_e32 v40, v235, v44, vcc
	ds_read_b128 v[220:223], v55 offset:39360
	s_waitcnt lgkmcnt(4)
	v_mfma_f32_16x16x32_bf16 v[50:53], v[216:219], v[10:13], v[50:53]
	v_add_u32_e32 v151, 29, v149
	v_cmp_le_u32_e32 vcc, v151, v148
	s_nop 1
	v_cndmask_b32_e32 v41, v235, v45, vcc
	v_max3_f32 v159, v159, v40, v41
	s_nop 0
	s_waitcnt lgkmcnt(3)
	v_mfma_f32_16x16x32_bf16 v[6:9], v[204:207], v[6:9], 0
	v_add_u32_e32 v151, 16, v149
	v_cmp_le_u32_e32 vcc, v151, v148
	s_nop 1
	v_cndmask_b32_e32 v42, v235, v46, vcc
	s_nop 0
	s_waitcnt lgkmcnt(2)
	v_mfma_f32_16x16x32_bf16 v[6:9], v[208:211], v[14:17], v[6:9]
	v_add_u32_e32 v151, 15, v149
	v_cmp_le_u32_e32 vcc, v151, v148
	s_nop 1
	v_cndmask_b32_e32 v43, v235, v47, vcc
	v_max3_f32 v159, v159, v42, v43
	s_nop 0
	s_waitcnt lgkmcnt(1)
	v_mfma_f32_16x16x32_bf16 v[2:5], v[212:215], v[2:5], v[6:9]
	v_add_u32_e32 v151, 14, v149
	v_cmp_le_u32_e32 vcc, v151, v148
	s_nop 1
	v_cndmask_b32_e32 v44, v235, v48, vcc
	s_nop 4
	s_nop 0
	s_waitcnt lgkmcnt(0)
	v_mfma_f32_16x16x32_bf16 v[2:5], v[220:223], v[10:13], v[2:5]
	v_add_u32_e32 v151, 13, v149
	v_cmp_le_u32_e32 vcc, v151, v148
	s_nop 1
	v_cndmask_b32_e32 v45, v235, v49, vcc
	v_max3_f32 v159, v159, v44, v45
	v_cmp_le_u32_e32 vcc, v149, v148
	s_nop 1
	v_cndmask_b32_e32 v46, v235, v50, vcc
	v_add_u32_e32 v151, -1, v149
	v_cmp_le_u32_e32 vcc, v151, v148
	s_nop 1
	v_cndmask_b32_e32 v47, v235, v51, vcc
	v_max3_f32 v159, v159, v46, v47
	v_add_u32_e32 v151, -2, v149
	v_cmp_le_u32_e32 vcc, v151, v148
	s_nop 1
	v_cndmask_b32_e32 v48, v235, v52, vcc
	v_add_u32_e32 v151, -3, v149
	v_cmp_le_u32_e32 vcc, v151, v148
	s_nop 1
	v_cndmask_b32_e32 v49, v235, v53, vcc
	v_max3_f32 v159, v159, v48, v49
	v_add_u32_e32 v151, -16, v149
	v_cmp_le_u32_e32 vcc, v151, v148
	s_nop 1
	v_cndmask_b32_e32 v50, v235, v2, vcc
	v_subrev_u32_e32 v151, 17, v149
	v_cmp_le_u32_e32 vcc, v151, v148
	s_nop 1
	v_cndmask_b32_e32 v51, v235, v3, vcc
	v_max3_f32 v159, v159, v50, v51
	v_subrev_u32_e32 v151, 18, v149
	v_cmp_le_u32_e32 vcc, v151, v148
	s_nop 1
	v_cndmask_b32_e32 v52, v235, v4, vcc
	v_subrev_u32_e32 v151, 19, v149
	v_cmp_le_u32_e32 vcc, v151, v148
	s_nop 1
	v_cndmask_b32_e32 v53, v235, v5, vcc
	v_max3_f32 v2, v159, v52, v53
	v_mov_b32_e32 v9, v160
	v_mov_b32_e32 v8, v161
	v_mov_b32_e32 v12, v162
	v_mov_b32_e32 v13, v163
	v_mov_b32_e32 v14, v164
	v_mov_b32_e32 v15, v165
	v_mov_b32_e32 v16, v168
	v_mov_b32_e32 v17, v169
	v_mov_b32_e32 v55, v150
	v_readlane_b32 s5, v255, 16
	v_and_b32_e32 v4, 64, v230
	v_xor_b32_e32 v3, 16, v230
	v_add_u32_e32 v4, 64, v4
	v_cmp_lt_i32_e32 vcc, v3, v4
	s_nop 1
	v_cndmask_b32_e32 v3, v230, v3, vcc
	v_lshlrev_b32_e32 v56, 2, v3
	v_mov_b32_e32 v3, v2
	s_nop 1
	v_permlane16_swap_b32_e32 v3, v2
	s_nop 1
	s_waitcnt lgkmcnt(0)
; #define LAS __attribute__((address_space(3)))
; __device__ __forceinline__ unsigned cvt_pk_bf16(float lo, float hi) { unsigned r; asm volatile("v_cvt_pk_bf16_f32 %0, %1, %2" : "=v"(r) : "v"(lo), "v"(hi)); return r; }
; __device__ __forceinline__ void attn_item(const Params& P, int half, int item, LAS unsigned char* lds, unsigned* ctr) {
;     ...
;     mx = fmaxf(mx, __shfl_xor(mx, 16)); mx = fmaxf(mx, __shfl_xor(mx, 32));
;     float den = 0.f;
; #pragma unroll
;     for (int jt = 0; jt < 10; ++jt) { const f32x4 d = S[jt] - mx; f32x4 p; p[0] = __builtin_amdgcn_exp2f(d[0]); p[1] = __builtin_amdgcn_exp2f(d[1]); p[2] = __builtin_amdgcn_exp2f(d[2]); p[3] = __builtin_amdgcn_exp2f(d[3]);
;         S[jt] = p; den += (p[0] + p[1]) + (p[2] + p[3]); }
;     den += __shfl_xor(den, 16); den += __shfl_xor(den, 32);
;     bf16x8 Pf[5];
; #pragma unroll
;     for (int k5 = 0; k5 < 5; ++k5) { u32x4 pw; pw.x = cvt_pk_bf16(S[2 * k5][0], S[2 * k5][1]); pw.y = cvt_pk_bf16(S[2 * k5][2], S[2 * k5][3]); pw.z = cvt_pk_bf16(S[2 * k5 + 1][0], S[2 * k5 + 1][1]); pw.w = cvt_pk_bf16(S[2 * k5 + 1][2], S[2 * k5 + 1][3]); Pf[k5] = as_bf16x8(pw); }
;     const float inv = 1.0f / den;
;     bf16_t* op = Z + (size_t)qrow * ZC + colq + 4 * g;
; #pragma unroll
;     for (int dt = 0; dt < 8; ++dt) {
;         f32x4 O = (f32x4){0.f, 0.f, 0.f, 0.f};
;         const LAS unsigned char* vr = Vt + (dt * 16 + c) * VSTR + (m0 + 4 * g) * 2;
; #pragma unroll
;         for (int k5 = 0; k5 < 5; ++k5) { const u32x2 lo = *(const LAS u32x2*)(vr + k5 * 64), hi = *(const LAS u32x2*)(vr + k5 * 64 + 32);
;             const bf16x8 a = as_bf16x8((u32x4){lo.x, lo.y, hi.x, hi.y}); O = __builtin_amdgcn_mfma_f32_16x16x32_bf16(a, Pf[k5], O, 0, 0, 0); }
	v_max_f32_e32 v3, v3, v3
	v_max_f32_e32 v2, v2, v3
	v_xor_b32_e32 v3, 32, v230
	v_cmp_lt_i32_e32 vcc, v3, v4
	s_nop 1
	v_cndmask_b32_e32 v3, v230, v3, vcc
	v_lshlrev_b32_e32 v57, 2, v3
	v_mov_b32_e32 v3, v2
	s_nop 1
	v_permlane32_swap_b32_e32 v3, v2
	s_nop 1
	s_waitcnt lgkmcnt(0)
	v_max_f32_e32 v3, v3, v3
	v_max_f32_e32 v24, v2, v3
	v_sub_f32_e32 v2, v13, v24
	v_sub_f32_e32 v3, v12, v24
	v_sub_f32_e32 v5, v8, v24
	v_sub_f32_e32 v4, v9, v24
	v_exp_f32_e32 v4, v4
	v_exp_f32_e32 v6, v5
	v_exp_f32_e32 v5, v3
	v_exp_f32_e32 v7, v2
	v_sub_f32_e32 v9, v16, v24
	v_sub_f32_e32 v10, v15, v24
	v_sub_f32_e32 v8, v14, v24
	v_pk_add_f32 v[2:3], v[4:5], v[6:7]
	v_exp_f32_e32 v8, v8
	v_add_f32_e32 v2, v2, v3
	v_add_f32_e32 v3, 0, v2
	v_sub_f32_e32 v2, v17, v24
	v_exp_f32_e32 v10, v10
	v_exp_f32_e32 v9, v9
	v_exp_f32_e32 v11, v2
	v_sub_f32_e32 v2, v21, v24
	v_sub_f32_e32 v14, v19, v24
	v_sub_f32_e32 v15, v18, v24
	v_pk_add_f32 v[12:13], v[8:9], v[10:11]
	v_exp_f32_e32 v58, v15
	v_pk_add_f32 v[12:13], v[12:13], v[12:13] op_sel_hi:[0,1]
	v_sub_f32_e32 v12, v20, v24
	v_exp_f32_e32 v59, v14
	v_exp_f32_e32 v60, v12
	v_exp_f32_e32 v61, v2
	v_sub_f32_e32 v2, v27, v24
	v_sub_f32_e32 v12, v26, v24
	v_sub_f32_e32 v14, v25, v24
	v_sub_f32_e32 v15, v22, v24
	v_exp_f32_e32 v16, v15
	v_exp_f32_e32 v22, v14
	v_exp_f32_e32 v12, v12
	v_exp_f32_e32 v2, v2
	v_add_f32_e32 v17, v58, v59
	v_add_f32_e32 v23, v60, v61
	v_pk_add_f32 v[14:15], v[16:17], v[22:23]
	v_pk_add_f32 v[18:19], v[12:13], v[2:3]
	v_sub_f32_e32 v3, v31, v24
	v_pk_add_f32 v[14:15], v[14:15], v[18:19]
	v_sub_f32_e32 v13, v30, v24
	v_pk_add_f32 v[26:27], v[14:15], v[14:15] op_sel_hi:[0,1]
	v_sub_f32_e32 v14, v29, v24
	v_sub_f32_e32 v15, v28, v24
	v_exp_f32_e32 v28, v15
	v_exp_f32_e32 v30, v14
	v_exp_f32_e32 v29, v13
	v_exp_f32_e32 v31, v3
	v_sub_f32_e32 v3, v37, v24
	v_sub_f32_e32 v13, v36, v24
	v_exp_f32_e32 v13, v13
	v_pk_add_f32 v[14:15], v[28:29], v[30:31]
	v_exp_f32_e32 v3, v3
	v_pk_add_f32 v[32:33], v[14:15], v[14:15] op_sel_hi:[0,1]
	v_sub_f32_e32 v14, v35, v24
	v_sub_f32_e32 v15, v34, v24
	v_exp_f32_e32 v23, v15
	v_exp_f32_e32 v25, v14
	v_sub_f32_e32 v14, v41, v24
	v_sub_f32_e32 v15, v40, v24
	v_sub_f32_e32 v17, v39, v24
	v_sub_f32_e32 v18, v38, v24
	v_exp_f32_e32 v34, v18
	v_exp_f32_e32 v36, v17
	v_exp_f32_e32 v32, v15
	v_exp_f32_e32 v26, v14
	v_add_f32_e32 v35, v23, v25
	v_add_f32_e32 v37, v13, v3
	v_pk_add_f32 v[14:15], v[34:35], v[36:37]
	v_pk_add_f32 v[18:19], v[32:33], v[26:27]
	v_sub_f32_e32 v17, v43, v24
	v_pk_add_f32 v[14:15], v[14:15], v[18:19]
	v_sub_f32_e32 v18, v42, v24
	v_pk_add_f32 v[38:39], v[14:15], v[14:15] op_sel_hi:[0,1]
	v_sub_f32_e32 v14, v45, v24
	v_sub_f32_e32 v15, v44, v24
	v_exp_f32_e32 v40, v18
	v_exp_f32_e32 v42, v17
	v_exp_f32_e32 v41, v15
	v_exp_f32_e32 v43, v14
	v_sub_f32_e32 v17, v47, v24
	v_sub_f32_e32 v18, v46, v24
	v_exp_f32_e32 v27, v18
	v_pk_add_f32 v[14:15], v[40:41], v[42:43]
	v_exp_f32_e32 v33, v17
	v_pk_add_f32 v[44:45], v[14:15], v[14:15] op_sel_hi:[0,1]
	v_sub_f32_e32 v14, v49, v24
	v_sub_f32_e32 v15, v48, v24
	v_exp_f32_e32 v35, v15
	v_exp_f32_e32 v37, v14
	v_sub_f32_e32 v14, v53, v24
	v_sub_f32_e32 v15, v52, v24
	v_sub_f32_e32 v17, v51, v24
	v_sub_f32_e32 v18, v50, v24
	v_exp_f32_e32 v46, v18
	v_exp_f32_e32 v48, v17
	v_exp_f32_e32 v44, v15
	v_exp_f32_e32 v38, v14
	v_add_f32_e32 v47, v27, v33
	v_add_f32_e32 v49, v35, v37
	v_pk_add_f32 v[14:15], v[46:47], v[48:49]
	v_pk_add_f32 v[18:19], v[44:45], v[38:39]
	s_nop 0
	v_pk_add_f32 v[14:15], v[14:15], v[18:19]
	v_cvt_pk_bf16_f32 v18, v4, v6
	v_cvt_pk_bf16_f32 v19, v5, v7
	v_cvt_pk_bf16_f32 v20, v8, v10
	v_cvt_pk_bf16_f32 v21, v9, v11
	s_nop 0
	v_add_f32_e32 v14, v14, v15
	v_mov_b32_e32 v15, v14
	s_nop 1
	v_permlane16_swap_b32_e32 v15, v14
	s_nop 1
	s_waitcnt lgkmcnt(0)
	v_add_f32_e32 v39, v14, v15
	ds_bpermute_b32 v45, v57, v39
	v_cvt_pk_bf16_f32 v14, v58, v59
	v_cvt_pk_bf16_f32 v15, v60, v61
	v_cvt_pk_bf16_f32 v16, v16, v22
	v_cvt_pk_bf16_f32 v17, v12, v2
	v_cvt_pk_bf16_f32 v10, v28, v30
	v_cvt_pk_bf16_f32 v11, v29, v31
	v_cvt_pk_bf16_f32 v12, v23, v25
	s_waitcnt lgkmcnt(0)
	v_add_f32_e32 v25, v39, v45
	v_div_scale_f32 v22, s[6:7], v25, v25, 1.0
	v_rcp_f32_e32 v23, v22
	v_cvt_pk_bf16_f32 v13, v13, v3
	v_cvt_pk_bf16_f32 v6, v34, v36
	v_cvt_pk_bf16_f32 v7, v32, v26
	v_cvt_pk_bf16_f32 v8, v40, v42
	v_cvt_pk_bf16_f32 v9, v41, v43
	s_nop 0
	v_fma_f32 v26, -v22, v23, 1.0
	v_fmac_f32_e32 v23, v26, v23
	v_div_scale_f32 v26, vcc, 1.0, v25, 1.0
	v_cvt_pk_bf16_f32 v2, v27, v33
	v_mul_f32_e32 v27, v26, v23
	v_fma_f32 v28, -v22, v27, v26
	v_fmac_f32_e32 v27, v28, v23
	v_fma_f32 v22, -v22, v27, v26
	v_div_fmas_f32 v22, v22, v23, v27
	v_lshlrev_b32_e32 v27, 1, v55
	v_mul_u32_u24_e32 v28, 0x210, v54
	v_add3_u32 v27, s5, v27, v28
	v_cvt_pk_bf16_f32 v3, v35, v37
	v_cvt_pk_bf16_f32 v4, v46, v48
	v_cvt_pk_bf16_f32 v5, v44, v38
	ds_read2_b64 v[204:207], v27 offset1:4
	ds_read2_b64 v[208:211], v27 offset0:8 offset1:12
	ds_read2_b64 v[212:215], v27 offset0:16 offset1:20
	ds_read2_b64 v[216:219], v27 offset0:24 offset1:28
	ds_read2_b64 v[220:223], v27 offset0:32 offset1:36
	v_add_u32_e32 v156, 0x2100, v27
	ds_read2_b64 v[176:179], v156 offset1:4
	ds_read2_b64 v[180:183], v156 offset0:8 offset1:12
	ds_read2_b64 v[184:187], v156 offset0:16 offset1:20
	ds_read2_b64 v[188:191], v156 offset0:24 offset1:28
	ds_read2_b64 v[172:175], v156 offset0:32 offset1:36
	s_waitcnt lgkmcnt(9)
	v_mfma_f32_16x16x32_bf16 v[28:31], v[204:207], v[18:21], 0
	v_div_fixup_f32 v26, v22, v25, 1.0
	v_lshl_add_u64 v[22:23], v[130:131], 0, v[194:195]
	v_and_b32_e32 v192, 16, v230
	v_lshrrev_b32_e32 v193, 1, v192
	v_add_u32_e32 v192, v192, v193
	v_mov_b32_e32 v193, 0
	v_lshl_add_u64 v[192:193], v[22:23], 0, v[192:193]
	s_waitcnt lgkmcnt(8)
; #define LAS __attribute__((address_space(3)))
; __device__ __forceinline__ unsigned cvt_pk_bf16(float lo, float hi) { unsigned r; asm volatile("v_cvt_pk_bf16_f32 %0, %1, %2" : "=v"(r) : "v"(lo), "v"(hi)); return r; }
; __device__ __forceinline__ void attn_item(const Params& P, int half, int item, LAS unsigned char* lds, unsigned* ctr) {
;     ...
;     const float inv = 1.0f / den;
;     bf16_t* op = Z + (size_t)qrow * ZC + colq + 4 * g;
; #pragma unroll
;     for (int dt = 0; dt < 8; ++dt) {
;         f32x4 O = (f32x4){0.f, 0.f, 0.f, 0.f};
;         const LAS unsigned char* vr = Vt + (dt * 16 + c) * VSTR + (m0 + 4 * g) * 2;
; #pragma unroll
;         for (int k5 = 0; k5 < 5; ++k5) { const u32x2 lo = *(const LAS u32x2*)(vr + k5 * 64), hi = *(const LAS u32x2*)(vr + k5 * 64 + 32);
;             const bf16x8 a = as_bf16x8((u32x4){lo.x, lo.y, hi.x, hi.y}); O = __builtin_amdgcn_mfma_f32_16x16x32_bf16(a, Pf[k5], O, 0, 0, 0); }
;         u32x2 ow; ow.x = cvt_pk_bf16(O[0] * inv, O[1] * inv); ow.y = cvt_pk_bf16(O[2] * inv, O[3] * inv);
;         *(u32x2*)(op + dt * 16) = ow;
;     }
	v_mfma_f32_16x16x32_bf16 v[28:31], v[208:211], v[14:17], v[28:31]
	v_cmp_eq_u32_e32 vcc, 0, v136
	s_waitcnt lgkmcnt(7)
	v_mfma_f32_16x16x32_bf16 v[28:31], v[212:215], v[10:13], v[28:31]
	s_waitcnt lgkmcnt(6)
	v_mfma_f32_16x16x32_bf16 v[28:31], v[216:219], v[6:9], v[28:31]
	s_waitcnt lgkmcnt(5)
	v_mfma_f32_16x16x32_bf16 v[28:31], v[220:223], v[2:5], v[28:31]
	v_add_u32_e32 v157, 0x4200, v27
	ds_read2_b64 v[204:207], v157 offset1:4
	ds_read2_b64 v[208:211], v157 offset0:8 offset1:12
	ds_read2_b64 v[212:215], v157 offset0:16 offset1:20
	ds_read2_b64 v[216:219], v157 offset0:24 offset1:28
	ds_read2_b64 v[220:223], v157 offset0:32 offset1:36
	s_waitcnt lgkmcnt(9)
	v_mfma_f32_16x16x32_bf16 v[152:155], v[176:179], v[18:21], 0
	s_nop 3
	v_mul_f32_e32 v28, v26, v28
	v_mul_f32_e32 v29, v26, v29
	s_waitcnt lgkmcnt(8)
	v_mfma_f32_16x16x32_bf16 v[152:155], v[180:183], v[14:17], v[152:155]
	v_cvt_pk_bf16_f32 v28, v28, v29
	v_mul_f32_e32 v29, v26, v30
	s_waitcnt lgkmcnt(7)
	v_mfma_f32_16x16x32_bf16 v[152:155], v[184:187], v[10:13], v[152:155]
	v_mul_f32_e32 v30, v26, v31
	v_cvt_pk_bf16_f32 v29, v29, v30
	s_waitcnt lgkmcnt(6)
	v_mfma_f32_16x16x32_bf16 v[152:155], v[188:191], v[6:9], v[152:155]
	v_mov_b32_e32 v248, v28
	v_mov_b32_e32 v249, v29
	s_waitcnt lgkmcnt(5)
	v_mfma_f32_16x16x32_bf16 v[152:155], v[172:175], v[2:5], v[152:155]
	v_add_u32_e32 v156, 0x6300, v27
	ds_read2_b64 v[176:179], v156 offset1:4
	ds_read2_b64 v[180:183], v156 offset0:8 offset1:12
	ds_read2_b64 v[184:187], v156 offset0:16 offset1:20
	ds_read2_b64 v[188:191], v156 offset0:24 offset1:28
	ds_read2_b64 v[172:175], v156 offset0:32 offset1:36
	s_waitcnt lgkmcnt(9)
	v_mfma_f32_16x16x32_bf16 v[28:31], v[204:207], v[18:21], 0
	s_nop 3
	v_mul_f32_e32 v152, v26, v152
	v_mul_f32_e32 v153, v26, v153
	s_waitcnt lgkmcnt(8)
	v_mfma_f32_16x16x32_bf16 v[28:31], v[208:211], v[14:17], v[28:31]
	v_cvt_pk_bf16_f32 v152, v152, v153
	v_mul_f32_e32 v153, v26, v154
	s_waitcnt lgkmcnt(7)
	v_mfma_f32_16x16x32_bf16 v[28:31], v[212:215], v[10:13], v[28:31]
	v_mul_f32_e32 v154, v26, v155
	v_cvt_pk_bf16_f32 v153, v153, v154
	s_waitcnt lgkmcnt(6)
	v_mfma_f32_16x16x32_bf16 v[28:31], v[216:219], v[6:9], v[28:31]
	v_mov_b32_e32 v154, v152
	v_mov_b32_e32 v155, v153
	v_mov_b32_e32 v152, v248
	v_mov_b32_e32 v153, v249
	s_waitcnt lgkmcnt(5)
	v_mfma_f32_16x16x32_bf16 v[28:31], v[220:223], v[2:5], v[28:31]
	s_nop 1
	v_permlane16_swap_b32_e32 v152, v154
	v_permlane16_swap_b32_e32 v153, v155
	global_store_dwordx4 v[192:193], v[152:155], off
	s_nop 1
	v_add_u32_e32 v157, 0x8400, v27
	ds_read2_b64 v[204:207], v157 offset1:4
	ds_read2_b64 v[208:211], v157 offset0:8 offset1:12
	ds_read2_b64 v[212:215], v157 offset0:16 offset1:20
	ds_read2_b64 v[216:219], v157 offset0:24 offset1:28
	ds_read2_b64 v[220:223], v157 offset0:32 offset1:36
	s_waitcnt lgkmcnt(9)
	v_mfma_f32_16x16x32_bf16 v[152:155], v[176:179], v[18:21], 0
	s_nop 3
	v_mul_f32_e32 v28, v26, v28
	v_mul_f32_e32 v29, v26, v29
	s_waitcnt lgkmcnt(8)
	v_mfma_f32_16x16x32_bf16 v[152:155], v[180:183], v[14:17], v[152:155]
	v_cvt_pk_bf16_f32 v28, v28, v29
	v_mul_f32_e32 v29, v26, v30
	s_waitcnt lgkmcnt(7)
	v_mfma_f32_16x16x32_bf16 v[152:155], v[184:187], v[10:13], v[152:155]
	v_mul_f32_e32 v30, v26, v31
	v_cvt_pk_bf16_f32 v29, v29, v30
	s_waitcnt lgkmcnt(6)
	v_mfma_f32_16x16x32_bf16 v[152:155], v[188:191], v[6:9], v[152:155]
	v_mov_b32_e32 v248, v28
	v_mov_b32_e32 v249, v29
	s_waitcnt lgkmcnt(5)
	v_mfma_f32_16x16x32_bf16 v[152:155], v[172:175], v[2:5], v[152:155]
	v_add_u32_e32 v156, 0xa500, v27
	ds_read2_b64 v[176:179], v156 offset1:4
	ds_read2_b64 v[180:183], v156 offset0:8 offset1:12
	ds_read2_b64 v[184:187], v156 offset0:16 offset1:20
	ds_read2_b64 v[188:191], v156 offset0:24 offset1:28
	ds_read2_b64 v[172:175], v156 offset0:32 offset1:36
	s_waitcnt lgkmcnt(9)
	v_mfma_f32_16x16x32_bf16 v[28:31], v[204:207], v[18:21], 0
	s_nop 3
	v_mul_f32_e32 v152, v26, v152
	v_mul_f32_e32 v153, v26, v153
	s_waitcnt lgkmcnt(8)
	v_mfma_f32_16x16x32_bf16 v[28:31], v[208:211], v[14:17], v[28:31]
	v_cvt_pk_bf16_f32 v152, v152, v153
	v_mul_f32_e32 v153, v26, v154
	s_waitcnt lgkmcnt(7)
	v_mfma_f32_16x16x32_bf16 v[28:31], v[212:215], v[10:13], v[28:31]
	v_mul_f32_e32 v154, v26, v155
	v_cvt_pk_bf16_f32 v153, v153, v154
	s_waitcnt lgkmcnt(6)
; #define LAS __attribute__((address_space(3)))
; __device__ __forceinline__ unsigned cvt_pk_bf16(float lo, float hi) { unsigned r; asm volatile("v_cvt_pk_bf16_f32 %0, %1, %2" : "=v"(r) : "v"(lo), "v"(hi)); return r; }
; __device__ __forceinline__ void attn_item(const Params& P, int half, int item, LAS unsigned char* lds, unsigned* ctr) {
;     ...
;     const float inv = 1.0f / den;
;     bf16_t* op = Z + (size_t)qrow * ZC + colq + 4 * g;
; #pragma unroll
;     for (int dt = 0; dt < 8; ++dt) {
;         f32x4 O = (f32x4){0.f, 0.f, 0.f, 0.f};
;         const LAS unsigned char* vr = Vt + (dt * 16 + c) * VSTR + (m0 + 4 * g) * 2;
; #pragma unroll
;         for (int k5 = 0; k5 < 5; ++k5) { const u32x2 lo = *(const LAS u32x2*)(vr + k5 * 64), hi = *(const LAS u32x2*)(vr + k5 * 64 + 32);
;             const bf16x8 a = as_bf16x8((u32x4){lo.x, lo.y, hi.x, hi.y}); O = __builtin_amdgcn_mfma_f32_16x16x32_bf16(a, Pf[k5], O, 0, 0, 0); }
;         u32x2 ow; ow.x = cvt_pk_bf16(O[0] * inv, O[1] * inv); ow.y = cvt_pk_bf16(O[2] * inv, O[3] * inv);
;         *(u32x2*)(op + dt * 16) = ow;
;     }
;     if (g == 0) LSE[(size_t)qrow * 12 + gi * 4 + hh] = (mx + __builtin_amdgcn_logf(den)) * 0.6931471805599453f;
	v_mfma_f32_16x16x32_bf16 v[28:31], v[216:219], v[6:9], v[28:31]
	v_mov_b32_e32 v154, v152
	v_mov_b32_e32 v155, v153
	v_mov_b32_e32 v152, v248
	v_mov_b32_e32 v153, v249
	s_waitcnt lgkmcnt(5)
	v_mfma_f32_16x16x32_bf16 v[28:31], v[220:223], v[2:5], v[28:31]
	s_nop 1
	v_permlane16_swap_b32_e32 v152, v154
	v_permlane16_swap_b32_e32 v153, v155
	global_store_dwordx4 v[192:193], v[152:155], off offset:64
	s_nop 1
	v_add_u32_e32 v157, 0xc600, v27
	ds_read2_b64 v[204:207], v157 offset1:4
	ds_read2_b64 v[208:211], v157 offset0:8 offset1:12
	ds_read2_b64 v[212:215], v157 offset0:16 offset1:20
	ds_read2_b64 v[216:219], v157 offset0:24 offset1:28
	ds_read2_b64 v[220:223], v157 offset0:32 offset1:36
	s_waitcnt lgkmcnt(9)
	v_mfma_f32_16x16x32_bf16 v[152:155], v[176:179], v[18:21], 0
	s_nop 3
	v_mul_f32_e32 v28, v26, v28
	v_mul_f32_e32 v29, v26, v29
	s_waitcnt lgkmcnt(8)
	v_mfma_f32_16x16x32_bf16 v[152:155], v[180:183], v[14:17], v[152:155]
	v_cvt_pk_bf16_f32 v28, v28, v29
	v_mul_f32_e32 v29, v26, v30
	s_waitcnt lgkmcnt(7)
	v_mfma_f32_16x16x32_bf16 v[152:155], v[184:187], v[10:13], v[152:155]
	v_mul_f32_e32 v30, v26, v31
	v_cvt_pk_bf16_f32 v29, v29, v30
	s_waitcnt lgkmcnt(6)
	v_mfma_f32_16x16x32_bf16 v[152:155], v[188:191], v[6:9], v[152:155]
	v_mov_b32_e32 v248, v28
	v_mov_b32_e32 v249, v29
	s_waitcnt lgkmcnt(5)
	v_mfma_f32_16x16x32_bf16 v[152:155], v[172:175], v[2:5], v[152:155]
	v_add_u32_e32 v156, 0xe700, v27
	ds_read2_b64 v[176:179], v156 offset1:4
	ds_read2_b64 v[180:183], v156 offset0:8 offset1:12
	ds_read2_b64 v[184:187], v156 offset0:16 offset1:20
	ds_read2_b64 v[188:191], v156 offset0:24 offset1:28
	ds_read2_b64 v[172:175], v156 offset0:32 offset1:36
	s_waitcnt lgkmcnt(9)
	v_mfma_f32_16x16x32_bf16 v[28:31], v[204:207], v[18:21], 0
	s_nop 3
	v_mul_f32_e32 v152, v26, v152
	v_mul_f32_e32 v153, v26, v153
	s_waitcnt lgkmcnt(8)
	v_mfma_f32_16x16x32_bf16 v[28:31], v[208:211], v[14:17], v[28:31]
	v_cvt_pk_bf16_f32 v152, v152, v153
	v_mul_f32_e32 v153, v26, v154
	s_waitcnt lgkmcnt(7)
	v_mfma_f32_16x16x32_bf16 v[28:31], v[212:215], v[10:13], v[28:31]
	v_mul_f32_e32 v154, v26, v155
	v_cvt_pk_bf16_f32 v153, v153, v154
	s_waitcnt lgkmcnt(6)
	v_mfma_f32_16x16x32_bf16 v[28:31], v[216:219], v[6:9], v[28:31]
	v_mov_b32_e32 v154, v152
	v_mov_b32_e32 v155, v153
	v_mov_b32_e32 v152, v248
	v_mov_b32_e32 v153, v249
	s_waitcnt lgkmcnt(5)
	v_mfma_f32_16x16x32_bf16 v[28:31], v[220:223], v[2:5], v[28:31]
	s_nop 1
	v_permlane16_swap_b32_e32 v152, v154
	v_permlane16_swap_b32_e32 v153, v155
	global_store_dwordx4 v[192:193], v[152:155], off offset:128
	s_nop 1
	s_waitcnt lgkmcnt(4)
	v_mfma_f32_16x16x32_bf16 v[152:155], v[176:179], v[18:21], 0
	s_nop 3
	v_mul_f32_e32 v28, v26, v28
	v_mul_f32_e32 v29, v26, v29
	s_waitcnt lgkmcnt(3)
	v_mfma_f32_16x16x32_bf16 v[152:155], v[180:183], v[14:17], v[152:155]
	v_cvt_pk_bf16_f32 v28, v28, v29
	v_mul_f32_e32 v29, v26, v30
	s_waitcnt lgkmcnt(2)
	v_mfma_f32_16x16x32_bf16 v[152:155], v[184:187], v[10:13], v[152:155]
	v_mul_f32_e32 v30, v26, v31
	v_cvt_pk_bf16_f32 v29, v29, v30
	s_waitcnt lgkmcnt(1)
	v_mfma_f32_16x16x32_bf16 v[152:155], v[188:191], v[6:9], v[152:155]
	v_mov_b32_e32 v248, v28
	v_mov_b32_e32 v249, v29
	s_waitcnt lgkmcnt(0)
	v_mfma_f32_16x16x32_bf16 v[152:155], v[172:175], v[2:5], v[152:155]
	s_nop 7
	s_nop 3
	v_mul_f32_e32 v152, v26, v152
	v_mul_f32_e32 v153, v26, v153
	v_cvt_pk_bf16_f32 v152, v152, v153
	v_mul_f32_e32 v153, v26, v154
	v_mul_f32_e32 v154, v26, v155
	v_cvt_pk_bf16_f32 v153, v153, v154
	v_mov_b32_e32 v154, v152
	v_mov_b32_e32 v155, v153
	v_mov_b32_e32 v152, v248
	v_mov_b32_e32 v153, v249
	s_nop 1
	v_permlane16_swap_b32_e32 v152, v154
	v_permlane16_swap_b32_e32 v153, v155
	global_store_dwordx4 v[192:193], v[152:155], off offset:192
	s_nop 1
	s_and_saveexec_b64 s[30:31], vcc
	s_cbranch_execz .LBB0_541
	v_log_f32_e32 v2, v25
	v_readlane_b32 s8, v251, 33
	s_lshl_b32 s6, s2, 2
	v_readlane_b32 s9, v251, 34
	v_add_f32_e32 v2, v24, v2
	s_ashr_i32 s7, s6, 31
	v_mul_f32_e32 v4, 0x3f317218, v2
	v_mad_i64_i32 v[2:3], s[8:9], v133, 48, s[8:9]
	v_lshl_add_u64 v[2:3], s[6:7], 2, v[2:3]
	s_lshl_b32 s20, s4, 2
	v_lshl_add_u64 v[2:3], v[2:3], 0, s[20:21]
	global_store_dword v[2:3], v4, off
